# prefetch helper lead reduced from 5 to 4 steps
# speedup vs baseline: 1.0030x; 1.0018x over previous
.Lpf_entry:
	s_cmp_lg_u32 s95, 0
	s_cbranch_scc1 .LBB0_496
	s_cmp_gt_u32 s2, 255
	s_cbranch_scc1 .LBB0_496
	s_add_i32 s0, s2, -72
	s_lshr_b32 s1, s0, 3
	s_and_b32 s3, s2, 7
	s_and_b32 s6, s1, 7
	s_lshl_b32 s7, s6, 3
	s_or_b32 s3, s3, s7
	s_lshr_b32 s1, s1, 3
	s_cmp_eq_u32 s6, 7
	s_cselect_b32 s7, 2, 3
	s_add_u32 s98, s54, 0x1ec04000
	s_addc_u32 s99, s55, 0
	s_lshl_b32 s8, s3, 8
	s_add_u32 s98, s98, s8
	s_addc_u32 s99, s99, 0
	s_lshr_b32 s8, s3, 1
	s_add_u32 s14, s54, 0x15c00000
	s_addc_u32 s15, s55, 0
	s_mov_b32 s9, 0xe000
	s_mov_b32 s12, 0x380000
	s_bitcmp1_b32 s3, 0
	s_cmov_b32 s9, 0x12000
	s_cmov_b32 s12, 0x480000
	s_cselect_b32 s14, s14, s52
	s_cselect_b32 s15, s15, s53
	s_mul_i32 s13, s12, s8
	s_add_u32 s12, s14, s13
	s_addc_u32 s13, s15, 0
	s_lshr_b32 s16, s9, 6
	s_cmp_eq_u32 s7, 2
	s_cbranch_scc1 .Lpf_nh2
	s_add_i32 s17, s16, 2
	s_mul_i32 s17, s17, 0xaaab
	s_lshr_b32 s17, s17, 17
	s_branch .Lpf_per

.Lpf_poll:
	global_load_dword v20, v0, s[98:99] sc1
	s_waitcnt vmcnt(0)
	v_readfirstlane_b32 s17, v20
	s_nop 3
	s_add_i32 s17, s17, 4
	s_min_u32 s17, s17, 63
	s_cmp_gt_u32 s6, s17
	s_cbranch_scc1 .Lpf_wait
